# GEMM1 epilogue: the 8 row-sum loads issued together at the top with counted vmcnt instead of one vmcnt(0) round trip per row group
# baseline (speedup 1.0000x reference)
.LBB0_124:
	s_ashr_i32 s19, s19, 8
	s_mul_i32 s30, s19, 60
	s_ashr_i32 s27, s26, 31
	s_ashr_i32 s31, s30, 31
	s_lshl_b64 s[26:27], s[26:27], 17
	s_lshl_b64 s[30:31], s[30:31], 17
	s_add_u32 s30, s10, s30
	v_lshlrev_b32_e32 v154, 9, v150
	s_addc_u32 s31, s11, s31
	v_and_b32_e32 v136, 0x19e00, v154
	v_lshl_add_u64 v[152:153], s[30:31], 0, v[136:137]
	v_lshl_add_u64 v[152:153], v[152:153], 0, s[26:27]
	v_mov_b32_e32 v149, v137
	v_ashrrev_i32_e32 v151, 31, v150
	v_lshl_add_u64 v[162:163], v[152:153], 0, v[148:149]
	v_lshl_add_u64 v[152:153], v[150:151], 3, s[8:9]
	global_load_dwordx2 v[170:171], v[152:153], off
	global_load_dwordx2 v[172:173], v[152:153], off offset:128
	global_load_dwordx2 v[174:175], v[152:153], off offset:256
	global_load_dwordx2 v[176:177], v[152:153], off offset:384
	global_load_dwordx2 v[178:179], v[152:153], off offset:1024
	global_load_dwordx2 v[180:181], v[152:153], off offset:1152
	global_load_dwordx2 v[182:183], v[152:153], off offset:1280
	global_load_dwordx2 v[184:185], v[152:153], off offset:1408
	s_waitcnt vmcnt(7)
	s_nop 1
	v_mov_b64_e32 v[164:165], v[170:171]
	v_ffbh_u32_e32 v136, v165
	v_min_u32_e32 v136, 32, v136
	v_lshlrev_b64 v[164:165], v136, v[164:165]
	v_min_u32_e32 v151, 1, v164
	v_or_b32_e32 v151, v165, v151
	v_cvt_f32_u32_e32 v151, v151
	v_sub_u32_e32 v136, 32, v136
	v_ldexp_f32 v136, v151, v136
	v_mul_f32_e32 v136, 0x33800000, v136
	v_fmamk_f32 v136, v136, 0x39800000, v161
	v_cmp_gt_f32_e32 vcc, s64, v136
	v_mul_f32_e32 v151, 0x4b800000, v136
	s_nop 0
	v_cndmask_b32_e32 v136, v136, v151, vcc
	v_rsq_f32_e32 v136, v136
	s_nop 0
	v_mul_f32_e32 v151, 0x45800000, v136
	v_cndmask_b32_e32 v136, v136, v151, vcc
	v_pk_mul_f32 v[126:127], v[126:127], v[136:137] op_sel_hi:[1,0]
	v_pk_mul_f32 v[124:125], v[124:125], v[136:137] op_sel_hi:[1,0]
	v_pk_mul_f32 v[164:165], v[122:123], v[136:137] op_sel_hi:[1,0]
	v_pk_mul_f32 v[122:123], v[120:121], v[136:137] op_sel_hi:[1,0]
	v_cvt_pk_bf16_f32 v120, v124, v125
	v_cvt_pk_bf16_f32 v121, v126, v127
	v_pk_mul_f32 v[116:117], v[116:117], v[136:137] op_sel_hi:[1,0]
	v_cvt_pk_bf16_f32 v122, v122, v123
	v_cvt_pk_bf16_f32 v123, v164, v165
	global_store_dwordx4 v[162:163], v[120:123], off
	v_pk_mul_f32 v[118:119], v[118:119], v[136:137] op_sel_hi:[1,0]
	s_nop 0
	v_pk_mul_f32 v[120:121], v[114:115], v[136:137] op_sel_hi:[1,0]
	v_pk_mul_f32 v[114:115], v[112:113], v[136:137] op_sel_hi:[1,0]
	v_cvt_pk_bf16_f32 v112, v116, v117
	v_cvt_pk_bf16_f32 v113, v118, v119
	s_nop 0
	v_cvt_pk_bf16_f32 v114, v114, v115
	v_cvt_pk_bf16_f32 v115, v120, v121
	global_store_dwordx4 v[162:163], v[112:115], off offset:256
	s_nop 1
	v_or_b32_e32 v112, 16, v150
	v_lshlrev_b32_e32 v113, 9, v112
	v_and_b32_e32 v136, 0x1be00, v113
	v_ashrrev_i32_e32 v113, 31, v112
	v_lshl_add_u64 v[112:113], v[112:113], 3, s[8:9]
	v_lshl_add_u64 v[114:115], s[30:31], 0, v[136:137]
	v_lshl_add_u64 v[114:115], v[114:115], 0, s[26:27]
	v_lshl_add_u64 v[114:115], v[114:115], 0, v[148:149]
	s_waitcnt vmcnt(8)
	s_nop 1
	v_mov_b64_e32 v[112:113], v[172:173]
	v_ffbh_u32_e32 v116, v113
	v_min_u32_e32 v116, 32, v116
	v_lshlrev_b64 v[112:113], v116, v[112:113]
	v_min_u32_e32 v112, 1, v112
	v_or_b32_e32 v112, v113, v112
	v_cvt_f32_u32_e32 v112, v112
	v_sub_u32_e32 v113, 32, v116
	v_ldexp_f32 v112, v112, v113
	v_mul_f32_e32 v112, 0x33800000, v112
	v_fmamk_f32 v112, v112, 0x39800000, v161
	v_cmp_gt_f32_e32 vcc, s64, v112
	v_mul_f32_e32 v113, 0x4b800000, v112
	s_nop 0
	v_cndmask_b32_e32 v112, v112, v113, vcc
	v_rsq_f32_e32 v112, v112
	s_nop 0
	v_mul_f32_e32 v113, 0x45800000, v112
	v_cndmask_b32_e32 v112, v112, v113, vcc
	v_pk_mul_f32 v[110:111], v[110:111], v[112:113] op_sel_hi:[1,0]
	v_pk_mul_f32 v[108:109], v[108:109], v[112:113] op_sel_hi:[1,0]
	v_pk_mul_f32 v[116:117], v[106:107], v[112:113] op_sel_hi:[1,0]
	v_pk_mul_f32 v[106:107], v[104:105], v[112:113] op_sel_hi:[1,0]
	v_cvt_pk_bf16_f32 v104, v108, v109
	v_cvt_pk_bf16_f32 v105, v110, v111
	v_pk_mul_f32 v[100:101], v[100:101], v[112:113] op_sel_hi:[1,0]
	v_cvt_pk_bf16_f32 v106, v106, v107
	v_cvt_pk_bf16_f32 v107, v116, v117
	global_store_dwordx4 v[114:115], v[104:107], off
	v_pk_mul_f32 v[102:103], v[102:103], v[112:113] op_sel_hi:[1,0]
	s_nop 0
	v_pk_mul_f32 v[104:105], v[98:99], v[112:113] op_sel_hi:[1,0]
	v_pk_mul_f32 v[98:99], v[96:97], v[112:113] op_sel_hi:[1,0]
	v_cvt_pk_bf16_f32 v96, v100, v101
	v_cvt_pk_bf16_f32 v97, v102, v103
	s_nop 0
	v_cvt_pk_bf16_f32 v98, v98, v99
	v_cvt_pk_bf16_f32 v99, v104, v105
	global_store_dwordx4 v[114:115], v[96:99], off offset:256
	s_nop 1
	v_or_b32_e32 v96, 32, v150
	v_lshlrev_b32_e32 v97, 9, v96
	v_and_b32_e32 v136, 0x1de00, v97
	v_ashrrev_i32_e32 v97, 31, v96
	v_lshl_add_u64 v[96:97], v[96:97], 3, s[8:9]
	v_lshl_add_u64 v[98:99], s[30:31], 0, v[136:137]
	v_lshl_add_u64 v[98:99], v[98:99], 0, s[26:27]
	v_lshl_add_u64 v[98:99], v[98:99], 0, v[148:149]
	s_waitcnt vmcnt(9)
	s_nop 1
	v_mov_b64_e32 v[96:97], v[174:175]
	v_ffbh_u32_e32 v100, v97
	v_min_u32_e32 v100, 32, v100
	v_lshlrev_b64 v[96:97], v100, v[96:97]
	v_min_u32_e32 v96, 1, v96
	v_or_b32_e32 v96, v97, v96
	v_cvt_f32_u32_e32 v96, v96
	v_sub_u32_e32 v97, 32, v100
	v_ldexp_f32 v96, v96, v97
	v_mul_f32_e32 v96, 0x33800000, v96
	v_fmamk_f32 v96, v96, 0x39800000, v161
	v_cmp_gt_f32_e32 vcc, s64, v96
	v_mul_f32_e32 v97, 0x4b800000, v96
	s_nop 0
	v_cndmask_b32_e32 v96, v96, v97, vcc
	v_rsq_f32_e32 v96, v96
	s_nop 0
	v_mul_f32_e32 v97, 0x45800000, v96
	v_cndmask_b32_e32 v96, v96, v97, vcc
	v_pk_mul_f32 v[94:95], v[94:95], v[96:97] op_sel_hi:[1,0]
	v_pk_mul_f32 v[92:93], v[92:93], v[96:97] op_sel_hi:[1,0]
	v_pk_mul_f32 v[100:101], v[90:91], v[96:97] op_sel_hi:[1,0]
	v_pk_mul_f32 v[90:91], v[88:89], v[96:97] op_sel_hi:[1,0]
	v_cvt_pk_bf16_f32 v88, v92, v93
	v_cvt_pk_bf16_f32 v89, v94, v95
	v_pk_mul_f32 v[86:87], v[86:87], v[96:97] op_sel_hi:[1,0]
	v_cvt_pk_bf16_f32 v90, v90, v91
	v_cvt_pk_bf16_f32 v91, v100, v101
	global_store_dwordx4 v[98:99], v[88:91], off
	v_pk_mul_f32 v[84:85], v[84:85], v[96:97] op_sel_hi:[1,0]
	s_nop 0
	v_pk_mul_f32 v[88:89], v[82:83], v[96:97] op_sel_hi:[1,0]
	v_pk_mul_f32 v[82:83], v[80:81], v[96:97] op_sel_hi:[1,0]
	v_cvt_pk_bf16_f32 v80, v84, v85
	v_cvt_pk_bf16_f32 v81, v86, v87
	s_nop 0
	v_cvt_pk_bf16_f32 v82, v82, v83
	v_cvt_pk_bf16_f32 v83, v88, v89
	global_store_dwordx4 v[98:99], v[80:83], off offset:256
	s_nop 1
	v_or_b32_e32 v82, 48, v150
	v_ashrrev_i32_e32 v83, 31, v82
	v_lshlrev_b32_e32 v80, 9, v82
	v_lshl_add_u64 v[82:83], v[82:83], 3, s[8:9]
	v_and_b32_e32 v136, 0x1fe00, v80
	v_lshl_add_u64 v[80:81], s[30:31], 0, v[136:137]
	v_lshl_add_u64 v[80:81], v[80:81], 0, s[26:27]
	v_lshl_add_u64 v[80:81], v[80:81], 0, v[148:149]
	s_waitcnt vmcnt(10)
	s_nop 1
	v_mov_b64_e32 v[82:83], v[176:177]
	v_ffbh_u32_e32 v84, v83
	v_min_u32_e32 v84, 32, v84
	v_lshlrev_b64 v[82:83], v84, v[82:83]
	v_min_u32_e32 v82, 1, v82
	v_or_b32_e32 v82, v83, v82
	v_cvt_f32_u32_e32 v82, v82
	v_sub_u32_e32 v83, 32, v84
	v_ldexp_f32 v82, v82, v83
	v_mul_f32_e32 v82, 0x33800000, v82
	v_fmamk_f32 v82, v82, 0x39800000, v161
	v_cmp_gt_f32_e32 vcc, s64, v82
	v_mul_f32_e32 v83, 0x4b800000, v82
	s_nop 0
	v_cndmask_b32_e32 v82, v82, v83, vcc
	v_rsq_f32_e32 v82, v82
	s_nop 0
	v_mul_f32_e32 v83, 0x45800000, v82
	v_cndmask_b32_e32 v82, v82, v83, vcc
	v_pk_mul_f32 v[78:79], v[78:79], v[82:83] op_sel_hi:[1,0]
	v_pk_mul_f32 v[76:77], v[76:77], v[82:83] op_sel_hi:[1,0]
	v_pk_mul_f32 v[84:85], v[74:75], v[82:83] op_sel_hi:[1,0]
	v_pk_mul_f32 v[74:75], v[72:73], v[82:83] op_sel_hi:[1,0]
	v_cvt_pk_bf16_f32 v72, v76, v77
	v_cvt_pk_bf16_f32 v73, v78, v79
	v_pk_mul_f32 v[70:71], v[70:71], v[82:83] op_sel_hi:[1,0]
	v_cvt_pk_bf16_f32 v74, v74, v75
	v_cvt_pk_bf16_f32 v75, v84, v85
	global_store_dwordx4 v[80:81], v[72:75], off
	v_pk_mul_f32 v[68:69], v[68:69], v[82:83] op_sel_hi:[1,0]
	s_nop 0
	v_pk_mul_f32 v[72:73], v[66:67], v[82:83] op_sel_hi:[1,0]
	v_pk_mul_f32 v[66:67], v[64:65], v[82:83] op_sel_hi:[1,0]
	v_cvt_pk_bf16_f32 v64, v68, v69
	v_cvt_pk_bf16_f32 v65, v70, v71
	s_nop 0
	v_cvt_pk_bf16_f32 v66, v66, v67
	v_cvt_pk_bf16_f32 v67, v72, v73
	global_store_dwordx4 v[80:81], v[64:67], off offset:256
	s_waitcnt vmcnt(11)
	s_nop 1
	v_mov_b64_e32 v[68:69], v[178:179]
	v_ffbh_u32_e32 v70, v69
	v_min_u32_e32 v70, 32, v70
	v_lshlrev_b64 v[68:69], v70, v[68:69]
	v_min_u32_e32 v68, 1, v68
	v_or_b32_e32 v68, v69, v68
	v_cvt_f32_u32_e32 v68, v68
	v_sub_u32_e32 v69, 32, v70
	v_add_u32_e32 v66, 0x80, v150
	v_lshrrev_b32_e32 v64, 8, v66
	v_ldexp_f32 v68, v68, v69
	v_mul_f32_e32 v68, 0x33800000, v68
	v_fmamk_f32 v68, v68, 0x39800000, v161
	v_cmp_gt_f32_e32 vcc, s64, v68
	v_mul_f32_e32 v69, 0x4b800000, v68
	v_mul_i32_i24_e32 v64, 60, v64
	v_cndmask_b32_e32 v68, v68, v69, vcc
	v_rsq_f32_e32 v68, v68
	v_ashrrev_i32_e32 v65, 31, v64
	v_lshlrev_b64 v[64:65], 17, v[64:65]
	v_lshlrev_b32_e32 v66, 9, v66
	v_lshl_add_u64 v[64:65], s[10:11], 0, v[64:65]
	v_and_b32_e32 v136, 0x19e00, v66
	v_lshl_add_u64 v[66:67], v[64:65], 0, v[136:137]
	v_mul_f32_e32 v69, 0x45800000, v68
	v_lshl_add_u64 v[66:67], v[66:67], 0, s[26:27]
	v_cndmask_b32_e32 v68, v68, v69, vcc
	v_lshl_add_u64 v[66:67], v[66:67], 0, v[148:149]
	v_pk_mul_f32 v[62:63], v[62:63], v[68:69] op_sel_hi:[1,0]
	v_pk_mul_f32 v[60:61], v[60:61], v[68:69] op_sel_hi:[1,0]
	v_pk_mul_f32 v[70:71], v[58:59], v[68:69] op_sel_hi:[1,0]
	v_pk_mul_f32 v[58:59], v[56:57], v[68:69] op_sel_hi:[1,0]
	v_cvt_pk_bf16_f32 v56, v60, v61
	v_cvt_pk_bf16_f32 v57, v62, v63
	v_pk_mul_f32 v[54:55], v[54:55], v[68:69] op_sel_hi:[1,0]
	v_cvt_pk_bf16_f32 v58, v58, v59
	v_cvt_pk_bf16_f32 v59, v70, v71
	global_store_dwordx4 v[66:67], v[56:59], off
	v_pk_mul_f32 v[52:53], v[52:53], v[68:69] op_sel_hi:[1,0]
	s_nop 0
	v_pk_mul_f32 v[56:57], v[50:51], v[68:69] op_sel_hi:[1,0]
	v_pk_mul_f32 v[50:51], v[48:49], v[68:69] op_sel_hi:[1,0]
	v_cvt_pk_bf16_f32 v48, v52, v53
	v_cvt_pk_bf16_f32 v49, v54, v55
	s_nop 0
	v_cvt_pk_bf16_f32 v50, v50, v51
	v_cvt_pk_bf16_f32 v51, v56, v57
	global_store_dwordx4 v[66:67], v[48:51], off offset:256
	s_waitcnt vmcnt(12)
	s_nop 1
	v_mov_b64_e32 v[50:51], v[180:181]
	v_ffbh_u32_e32 v52, v51
	v_min_u32_e32 v52, 32, v52
	v_lshlrev_b64 v[50:51], v52, v[50:51]
	v_min_u32_e32 v50, 1, v50
	v_or_b32_e32 v50, v51, v50
	v_cvt_f32_u32_e32 v50, v50
	v_sub_u32_e32 v51, 32, v52
	v_add_u32_e32 v48, 0x12000, v154
	v_and_b32_e32 v136, 0x1be00, v48
	v_ldexp_f32 v50, v50, v51
	v_mul_f32_e32 v50, 0x33800000, v50
	v_fmamk_f32 v50, v50, 0x39800000, v161
	v_cmp_gt_f32_e32 vcc, s64, v50
	v_mul_f32_e32 v51, 0x4b800000, v50
	v_lshl_add_u64 v[48:49], v[64:65], 0, v[136:137]
	v_cndmask_b32_e32 v50, v50, v51, vcc
	v_rsq_f32_e32 v50, v50
	v_lshl_add_u64 v[48:49], v[48:49], 0, s[26:27]
	v_lshl_add_u64 v[48:49], v[48:49], 0, v[148:149]
	v_mul_f32_e32 v51, 0x45800000, v50
	v_cndmask_b32_e32 v50, v50, v51, vcc
	v_pk_mul_f32 v[46:47], v[46:47], v[50:51] op_sel_hi:[1,0]
	v_pk_mul_f32 v[44:45], v[44:45], v[50:51] op_sel_hi:[1,0]
	v_pk_mul_f32 v[52:53], v[42:43], v[50:51] op_sel_hi:[1,0]
	v_pk_mul_f32 v[42:43], v[40:41], v[50:51] op_sel_hi:[1,0]
	v_cvt_pk_bf16_f32 v40, v44, v45
	v_cvt_pk_bf16_f32 v41, v46, v47
	v_pk_mul_f32 v[38:39], v[38:39], v[50:51] op_sel_hi:[1,0]
	v_cvt_pk_bf16_f32 v42, v42, v43
	v_cvt_pk_bf16_f32 v43, v52, v53
	global_store_dwordx4 v[48:49], v[40:43], off
	v_pk_mul_f32 v[36:37], v[36:37], v[50:51] op_sel_hi:[1,0]
	s_nop 0
	v_pk_mul_f32 v[40:41], v[34:35], v[50:51] op_sel_hi:[1,0]
	v_pk_mul_f32 v[34:35], v[32:33], v[50:51] op_sel_hi:[1,0]
	v_cvt_pk_bf16_f32 v32, v36, v37
	v_cvt_pk_bf16_f32 v33, v38, v39
	s_nop 0
	v_cvt_pk_bf16_f32 v34, v34, v35
	v_cvt_pk_bf16_f32 v35, v40, v41
	global_store_dwordx4 v[48:49], v[32:35], off offset:256
	s_waitcnt vmcnt(13)
	s_nop 1
	v_mov_b64_e32 v[34:35], v[182:183]
	v_ffbh_u32_e32 v36, v35
	v_min_u32_e32 v36, 32, v36
	v_lshlrev_b64 v[34:35], v36, v[34:35]
	v_min_u32_e32 v34, 1, v34
	v_or_b32_e32 v34, v35, v34
	v_cvt_f32_u32_e32 v34, v34
	v_sub_u32_e32 v35, 32, v36
	v_add_u32_e32 v32, 0x14000, v154
	v_and_b32_e32 v136, 0x1de00, v32
	v_ldexp_f32 v34, v34, v35
	v_mul_f32_e32 v34, 0x33800000, v34
	v_fmamk_f32 v34, v34, 0x39800000, v161
	v_cmp_gt_f32_e32 vcc, s64, v34
	v_mul_f32_e32 v35, 0x4b800000, v34
	v_lshl_add_u64 v[32:33], v[64:65], 0, v[136:137]
	v_cndmask_b32_e32 v34, v34, v35, vcc
	v_rsq_f32_e32 v34, v34
	v_lshl_add_u64 v[32:33], v[32:33], 0, s[26:27]
	v_lshl_add_u64 v[32:33], v[32:33], 0, v[148:149]
	v_mul_f32_e32 v35, 0x45800000, v34
	v_cndmask_b32_e32 v34, v34, v35, vcc
	v_pk_mul_f32 v[30:31], v[30:31], v[34:35] op_sel_hi:[1,0]
	v_pk_mul_f32 v[28:29], v[28:29], v[34:35] op_sel_hi:[1,0]
	v_pk_mul_f32 v[36:37], v[26:27], v[34:35] op_sel_hi:[1,0]
	v_pk_mul_f32 v[26:27], v[24:25], v[34:35] op_sel_hi:[1,0]
	v_cvt_pk_bf16_f32 v24, v28, v29
	v_cvt_pk_bf16_f32 v25, v30, v31
	v_pk_mul_f32 v[22:23], v[22:23], v[34:35] op_sel_hi:[1,0]
	v_cvt_pk_bf16_f32 v26, v26, v27
	v_cvt_pk_bf16_f32 v27, v36, v37
	global_store_dwordx4 v[32:33], v[24:27], off
	v_pk_mul_f32 v[20:21], v[20:21], v[34:35] op_sel_hi:[1,0]
	s_nop 0
	v_pk_mul_f32 v[24:25], v[18:19], v[34:35] op_sel_hi:[1,0]
	v_pk_mul_f32 v[18:19], v[16:17], v[34:35] op_sel_hi:[1,0]
	v_cvt_pk_bf16_f32 v16, v20, v21
	v_cvt_pk_bf16_f32 v17, v22, v23
	s_nop 0
	v_cvt_pk_bf16_f32 v18, v18, v19
	v_cvt_pk_bf16_f32 v19, v24, v25
	global_store_dwordx4 v[32:33], v[16:19], off offset:256
	s_waitcnt vmcnt(14)
	s_nop 1
	v_mov_b64_e32 v[18:19], v[184:185]
	v_ffbh_u32_e32 v20, v19
	v_min_u32_e32 v20, 32, v20
	v_lshlrev_b64 v[18:19], v20, v[18:19]
	v_min_u32_e32 v18, 1, v18
	v_or_b32_e32 v18, v19, v18
	v_cvt_f32_u32_e32 v18, v18
	v_sub_u32_e32 v19, 32, v20
	v_add_u32_e32 v16, 0x16000, v154
	v_and_b32_e32 v136, 0x1fe00, v16
	v_ldexp_f32 v18, v18, v19
	v_mul_f32_e32 v18, 0x33800000, v18
	v_fmamk_f32 v18, v18, 0x39800000, v161
	v_cmp_gt_f32_e32 vcc, s64, v18
	v_mul_f32_e32 v19, 0x4b800000, v18
	v_lshl_add_u64 v[16:17], v[64:65], 0, v[136:137]
	v_cndmask_b32_e32 v18, v18, v19, vcc
	v_rsq_f32_e32 v18, v18
	v_lshl_add_u64 v[16:17], v[16:17], 0, s[26:27]
	v_lshl_add_u64 v[16:17], v[16:17], 0, v[148:149]
	v_mul_f32_e32 v19, 0x45800000, v18
	v_cndmask_b32_e32 v18, v18, v19, vcc
	v_pk_mul_f32 v[14:15], v[14:15], v[18:19] op_sel_hi:[1,0]
	v_pk_mul_f32 v[12:13], v[12:13], v[18:19] op_sel_hi:[1,0]
	v_pk_mul_f32 v[20:21], v[10:11], v[18:19] op_sel_hi:[1,0]
	v_pk_mul_f32 v[10:11], v[8:9], v[18:19] op_sel_hi:[1,0]
	v_cvt_pk_bf16_f32 v8, v12, v13
	v_cvt_pk_bf16_f32 v9, v14, v15
	v_pk_mul_f32 v[6:7], v[6:7], v[18:19] op_sel_hi:[1,0]
	v_cvt_pk_bf16_f32 v10, v10, v11
	v_cvt_pk_bf16_f32 v11, v20, v21
	global_store_dwordx4 v[16:17], v[8:11], off
	v_pk_mul_f32 v[4:5], v[4:5], v[18:19] op_sel_hi:[1,0]
	s_nop 0
	v_pk_mul_f32 v[8:9], v[2:3], v[18:19] op_sel_hi:[1,0]
	v_pk_mul_f32 v[2:3], v[0:1], v[18:19] op_sel_hi:[1,0]
	v_cvt_pk_bf16_f32 v0, v4, v5
	v_cvt_pk_bf16_f32 v1, v6, v7
	s_nop 0
	v_cvt_pk_bf16_f32 v2, v2, v3
	v_cvt_pk_bf16_f32 v3, v8, v9
	global_store_dwordx4 v[16:17], v[0:3], off offset:256
	s_andn2_b64 vcc, exec, s[0:1]
	s_mov_b64 s[0:1], -1
	s_cbranch_vccnz .LBB0_107

.LBB0_1750:
	s_ashr_i32 s19, s19, 8
	s_mul_i32 s30, s19, 60
	s_ashr_i32 s27, s26, 31
	s_ashr_i32 s31, s30, 31
	s_lshl_b64 s[26:27], s[26:27], 17
	s_lshl_b64 s[30:31], s[30:31], 17
	s_add_u32 s30, s8, s30
	v_lshlrev_b32_e32 v154, 9, v150
	s_addc_u32 s31, s9, s31
	v_and_b32_e32 v136, 0x19e00, v154
	v_lshl_add_u64 v[152:153], s[30:31], 0, v[136:137]
	v_lshl_add_u64 v[152:153], v[152:153], 0, s[26:27]
	v_mov_b32_e32 v149, v137
	v_ashrrev_i32_e32 v151, 31, v150
	v_lshl_add_u64 v[162:163], v[152:153], 0, v[148:149]
	v_lshl_add_u64 v[152:153], v[150:151], 3, s[10:11]
	global_load_dwordx2 v[170:171], v[152:153], off
	global_load_dwordx2 v[172:173], v[152:153], off offset:128
	global_load_dwordx2 v[174:175], v[152:153], off offset:256
	global_load_dwordx2 v[176:177], v[152:153], off offset:384
	global_load_dwordx2 v[178:179], v[152:153], off offset:1024
	global_load_dwordx2 v[180:181], v[152:153], off offset:1152
	global_load_dwordx2 v[182:183], v[152:153], off offset:1280
	global_load_dwordx2 v[184:185], v[152:153], off offset:1408
	s_waitcnt vmcnt(7)
	s_nop 1
	v_mov_b64_e32 v[164:165], v[170:171]
	v_ffbh_u32_e32 v136, v165
	v_min_u32_e32 v136, 32, v136
	v_lshlrev_b64 v[164:165], v136, v[164:165]
	v_min_u32_e32 v151, 1, v164
	v_or_b32_e32 v151, v165, v151
	v_cvt_f32_u32_e32 v151, v151
	v_sub_u32_e32 v136, 32, v136
	v_ldexp_f32 v136, v151, v136
	v_mul_f32_e32 v136, 0x33800000, v136
	v_fmamk_f32 v136, v136, 0x39800000, v161
	v_cmp_gt_f32_e32 vcc, s64, v136
	v_mul_f32_e32 v151, 0x4b800000, v136
	s_nop 0
	v_cndmask_b32_e32 v136, v136, v151, vcc
	v_rsq_f32_e32 v136, v136
	s_nop 0
	v_mul_f32_e32 v151, 0x45800000, v136
	v_cndmask_b32_e32 v136, v136, v151, vcc
	v_pk_mul_f32 v[126:127], v[126:127], v[136:137] op_sel_hi:[1,0]
	v_pk_mul_f32 v[124:125], v[124:125], v[136:137] op_sel_hi:[1,0]
	v_pk_mul_f32 v[164:165], v[122:123], v[136:137] op_sel_hi:[1,0]
	v_pk_mul_f32 v[122:123], v[120:121], v[136:137] op_sel_hi:[1,0]
	v_cvt_pk_bf16_f32 v120, v124, v125
	v_cvt_pk_bf16_f32 v121, v126, v127
	v_pk_mul_f32 v[116:117], v[116:117], v[136:137] op_sel_hi:[1,0]
	v_cvt_pk_bf16_f32 v122, v122, v123
	v_cvt_pk_bf16_f32 v123, v164, v165
	global_store_dwordx4 v[162:163], v[120:123], off
	v_pk_mul_f32 v[118:119], v[118:119], v[136:137] op_sel_hi:[1,0]
	s_nop 0
	v_pk_mul_f32 v[120:121], v[114:115], v[136:137] op_sel_hi:[1,0]
	v_pk_mul_f32 v[114:115], v[112:113], v[136:137] op_sel_hi:[1,0]
	v_cvt_pk_bf16_f32 v112, v116, v117
	v_cvt_pk_bf16_f32 v113, v118, v119
	s_nop 0
	v_cvt_pk_bf16_f32 v114, v114, v115
	v_cvt_pk_bf16_f32 v115, v120, v121
	global_store_dwordx4 v[162:163], v[112:115], off offset:256
	s_nop 1
	v_or_b32_e32 v112, 16, v150
	v_lshlrev_b32_e32 v113, 9, v112
	v_and_b32_e32 v136, 0x1be00, v113
	v_ashrrev_i32_e32 v113, 31, v112
	v_lshl_add_u64 v[112:113], v[112:113], 3, s[10:11]
	v_lshl_add_u64 v[114:115], s[30:31], 0, v[136:137]
	v_lshl_add_u64 v[114:115], v[114:115], 0, s[26:27]
	v_lshl_add_u64 v[114:115], v[114:115], 0, v[148:149]
	s_waitcnt vmcnt(8)
	s_nop 1
	v_mov_b64_e32 v[112:113], v[172:173]
	v_ffbh_u32_e32 v116, v113
	v_min_u32_e32 v116, 32, v116
	v_lshlrev_b64 v[112:113], v116, v[112:113]
	v_min_u32_e32 v112, 1, v112
	v_or_b32_e32 v112, v113, v112
	v_cvt_f32_u32_e32 v112, v112
	v_sub_u32_e32 v113, 32, v116
	v_ldexp_f32 v112, v112, v113
	v_mul_f32_e32 v112, 0x33800000, v112
	v_fmamk_f32 v112, v112, 0x39800000, v161
	v_cmp_gt_f32_e32 vcc, s64, v112
	v_mul_f32_e32 v113, 0x4b800000, v112
	s_nop 0
	v_cndmask_b32_e32 v112, v112, v113, vcc
	v_rsq_f32_e32 v112, v112
	s_nop 0
	v_mul_f32_e32 v113, 0x45800000, v112
	v_cndmask_b32_e32 v112, v112, v113, vcc
	v_pk_mul_f32 v[110:111], v[110:111], v[112:113] op_sel_hi:[1,0]
	v_pk_mul_f32 v[108:109], v[108:109], v[112:113] op_sel_hi:[1,0]
	v_pk_mul_f32 v[116:117], v[106:107], v[112:113] op_sel_hi:[1,0]
	v_pk_mul_f32 v[106:107], v[104:105], v[112:113] op_sel_hi:[1,0]
	v_cvt_pk_bf16_f32 v104, v108, v109
	v_cvt_pk_bf16_f32 v105, v110, v111
	v_pk_mul_f32 v[100:101], v[100:101], v[112:113] op_sel_hi:[1,0]
	v_cvt_pk_bf16_f32 v106, v106, v107
	v_cvt_pk_bf16_f32 v107, v116, v117
	global_store_dwordx4 v[114:115], v[104:107], off
	v_pk_mul_f32 v[102:103], v[102:103], v[112:113] op_sel_hi:[1,0]
	s_nop 0
	v_pk_mul_f32 v[104:105], v[98:99], v[112:113] op_sel_hi:[1,0]
	v_pk_mul_f32 v[98:99], v[96:97], v[112:113] op_sel_hi:[1,0]
	v_cvt_pk_bf16_f32 v96, v100, v101
	v_cvt_pk_bf16_f32 v97, v102, v103
	s_nop 0
	v_cvt_pk_bf16_f32 v98, v98, v99
	v_cvt_pk_bf16_f32 v99, v104, v105
	global_store_dwordx4 v[114:115], v[96:99], off offset:256
	s_nop 1
	v_or_b32_e32 v96, 32, v150
	v_lshlrev_b32_e32 v97, 9, v96
	v_and_b32_e32 v136, 0x1de00, v97
	v_ashrrev_i32_e32 v97, 31, v96
	v_lshl_add_u64 v[96:97], v[96:97], 3, s[10:11]
	v_lshl_add_u64 v[98:99], s[30:31], 0, v[136:137]
	v_lshl_add_u64 v[98:99], v[98:99], 0, s[26:27]
	v_lshl_add_u64 v[98:99], v[98:99], 0, v[148:149]
	s_waitcnt vmcnt(9)
	s_nop 1
	v_mov_b64_e32 v[96:97], v[174:175]
	v_ffbh_u32_e32 v100, v97
	v_min_u32_e32 v100, 32, v100
	v_lshlrev_b64 v[96:97], v100, v[96:97]
	v_min_u32_e32 v96, 1, v96
	v_or_b32_e32 v96, v97, v96
	v_cvt_f32_u32_e32 v96, v96
	v_sub_u32_e32 v97, 32, v100
	v_ldexp_f32 v96, v96, v97
	v_mul_f32_e32 v96, 0x33800000, v96
	v_fmamk_f32 v96, v96, 0x39800000, v161
	v_cmp_gt_f32_e32 vcc, s64, v96
	v_mul_f32_e32 v97, 0x4b800000, v96
	s_nop 0
	v_cndmask_b32_e32 v96, v96, v97, vcc
	v_rsq_f32_e32 v96, v96
	s_nop 0
	v_mul_f32_e32 v97, 0x45800000, v96
	v_cndmask_b32_e32 v96, v96, v97, vcc
	v_pk_mul_f32 v[94:95], v[94:95], v[96:97] op_sel_hi:[1,0]
	v_pk_mul_f32 v[92:93], v[92:93], v[96:97] op_sel_hi:[1,0]
	v_pk_mul_f32 v[100:101], v[90:91], v[96:97] op_sel_hi:[1,0]
	v_pk_mul_f32 v[90:91], v[88:89], v[96:97] op_sel_hi:[1,0]
	v_cvt_pk_bf16_f32 v88, v92, v93
	v_cvt_pk_bf16_f32 v89, v94, v95
	v_pk_mul_f32 v[86:87], v[86:87], v[96:97] op_sel_hi:[1,0]
	v_cvt_pk_bf16_f32 v90, v90, v91
	v_cvt_pk_bf16_f32 v91, v100, v101
	global_store_dwordx4 v[98:99], v[88:91], off
	v_pk_mul_f32 v[84:85], v[84:85], v[96:97] op_sel_hi:[1,0]
	s_nop 0
	v_pk_mul_f32 v[88:89], v[82:83], v[96:97] op_sel_hi:[1,0]
	v_pk_mul_f32 v[82:83], v[80:81], v[96:97] op_sel_hi:[1,0]
	v_cvt_pk_bf16_f32 v80, v84, v85
	v_cvt_pk_bf16_f32 v81, v86, v87
	s_nop 0
	v_cvt_pk_bf16_f32 v82, v82, v83
	v_cvt_pk_bf16_f32 v83, v88, v89
	global_store_dwordx4 v[98:99], v[80:83], off offset:256
	s_nop 1
	v_or_b32_e32 v82, 48, v150
	v_ashrrev_i32_e32 v83, 31, v82
	v_lshlrev_b32_e32 v80, 9, v82
	v_lshl_add_u64 v[82:83], v[82:83], 3, s[10:11]
	v_and_b32_e32 v136, 0x1fe00, v80
	v_lshl_add_u64 v[80:81], s[30:31], 0, v[136:137]
	v_lshl_add_u64 v[80:81], v[80:81], 0, s[26:27]
	v_lshl_add_u64 v[80:81], v[80:81], 0, v[148:149]
	s_waitcnt vmcnt(10)
	s_nop 1
	v_mov_b64_e32 v[82:83], v[176:177]
	v_ffbh_u32_e32 v84, v83
	v_min_u32_e32 v84, 32, v84
	v_lshlrev_b64 v[82:83], v84, v[82:83]
	v_min_u32_e32 v82, 1, v82
	v_or_b32_e32 v82, v83, v82
	v_cvt_f32_u32_e32 v82, v82
	v_sub_u32_e32 v83, 32, v84
	v_ldexp_f32 v82, v82, v83
	v_mul_f32_e32 v82, 0x33800000, v82
	v_fmamk_f32 v82, v82, 0x39800000, v161
	v_cmp_gt_f32_e32 vcc, s64, v82
	v_mul_f32_e32 v83, 0x4b800000, v82
	s_nop 0
	v_cndmask_b32_e32 v82, v82, v83, vcc
	v_rsq_f32_e32 v82, v82
	s_nop 0
	v_mul_f32_e32 v83, 0x45800000, v82
	v_cndmask_b32_e32 v82, v82, v83, vcc
	v_pk_mul_f32 v[78:79], v[78:79], v[82:83] op_sel_hi:[1,0]
	v_pk_mul_f32 v[76:77], v[76:77], v[82:83] op_sel_hi:[1,0]
	v_pk_mul_f32 v[84:85], v[74:75], v[82:83] op_sel_hi:[1,0]
	v_pk_mul_f32 v[74:75], v[72:73], v[82:83] op_sel_hi:[1,0]
	v_cvt_pk_bf16_f32 v72, v76, v77
	v_cvt_pk_bf16_f32 v73, v78, v79
	v_pk_mul_f32 v[70:71], v[70:71], v[82:83] op_sel_hi:[1,0]
	v_cvt_pk_bf16_f32 v74, v74, v75
	v_cvt_pk_bf16_f32 v75, v84, v85
	global_store_dwordx4 v[80:81], v[72:75], off
	v_pk_mul_f32 v[68:69], v[68:69], v[82:83] op_sel_hi:[1,0]
	s_nop 0
	v_pk_mul_f32 v[72:73], v[66:67], v[82:83] op_sel_hi:[1,0]
	v_pk_mul_f32 v[66:67], v[64:65], v[82:83] op_sel_hi:[1,0]
	v_cvt_pk_bf16_f32 v64, v68, v69
	v_cvt_pk_bf16_f32 v65, v70, v71
	s_nop 0
	v_cvt_pk_bf16_f32 v66, v66, v67
	v_cvt_pk_bf16_f32 v67, v72, v73
	global_store_dwordx4 v[80:81], v[64:67], off offset:256
	s_waitcnt vmcnt(11)
	s_nop 1
	v_mov_b64_e32 v[68:69], v[178:179]
	v_ffbh_u32_e32 v70, v69
	v_min_u32_e32 v70, 32, v70
	v_lshlrev_b64 v[68:69], v70, v[68:69]
	v_min_u32_e32 v68, 1, v68
	v_or_b32_e32 v68, v69, v68
	v_cvt_f32_u32_e32 v68, v68
	v_sub_u32_e32 v69, 32, v70
	v_add_u32_e32 v66, 0x80, v150
	v_lshrrev_b32_e32 v64, 8, v66
	v_ldexp_f32 v68, v68, v69
	v_mul_f32_e32 v68, 0x33800000, v68
	v_fmamk_f32 v68, v68, 0x39800000, v161
	v_cmp_gt_f32_e32 vcc, s64, v68
	v_mul_f32_e32 v69, 0x4b800000, v68
	v_mul_i32_i24_e32 v64, 60, v64
	v_cndmask_b32_e32 v68, v68, v69, vcc
	v_rsq_f32_e32 v68, v68
	v_ashrrev_i32_e32 v65, 31, v64
	v_lshlrev_b64 v[64:65], 17, v[64:65]
	v_lshlrev_b32_e32 v66, 9, v66
	v_lshl_add_u64 v[64:65], s[8:9], 0, v[64:65]
	v_and_b32_e32 v136, 0x19e00, v66
	v_lshl_add_u64 v[66:67], v[64:65], 0, v[136:137]
	v_mul_f32_e32 v69, 0x45800000, v68
	v_lshl_add_u64 v[66:67], v[66:67], 0, s[26:27]
	v_cndmask_b32_e32 v68, v68, v69, vcc
	v_lshl_add_u64 v[66:67], v[66:67], 0, v[148:149]
	v_pk_mul_f32 v[62:63], v[62:63], v[68:69] op_sel_hi:[1,0]
	v_pk_mul_f32 v[60:61], v[60:61], v[68:69] op_sel_hi:[1,0]
	v_pk_mul_f32 v[70:71], v[58:59], v[68:69] op_sel_hi:[1,0]
	v_pk_mul_f32 v[58:59], v[56:57], v[68:69] op_sel_hi:[1,0]
	v_cvt_pk_bf16_f32 v56, v60, v61
	v_cvt_pk_bf16_f32 v57, v62, v63
	v_pk_mul_f32 v[54:55], v[54:55], v[68:69] op_sel_hi:[1,0]
	v_cvt_pk_bf16_f32 v58, v58, v59
	v_cvt_pk_bf16_f32 v59, v70, v71
	global_store_dwordx4 v[66:67], v[56:59], off
	v_pk_mul_f32 v[52:53], v[52:53], v[68:69] op_sel_hi:[1,0]
	s_nop 0
	v_pk_mul_f32 v[56:57], v[50:51], v[68:69] op_sel_hi:[1,0]
	v_pk_mul_f32 v[50:51], v[48:49], v[68:69] op_sel_hi:[1,0]
	v_cvt_pk_bf16_f32 v48, v52, v53
	v_cvt_pk_bf16_f32 v49, v54, v55
	s_nop 0
	v_cvt_pk_bf16_f32 v50, v50, v51
	v_cvt_pk_bf16_f32 v51, v56, v57
	global_store_dwordx4 v[66:67], v[48:51], off offset:256
	s_waitcnt vmcnt(12)
	s_nop 1
	v_mov_b64_e32 v[50:51], v[180:181]
	v_ffbh_u32_e32 v52, v51
	v_min_u32_e32 v52, 32, v52
	v_lshlrev_b64 v[50:51], v52, v[50:51]
	v_min_u32_e32 v50, 1, v50
	v_or_b32_e32 v50, v51, v50
	v_cvt_f32_u32_e32 v50, v50
	v_sub_u32_e32 v51, 32, v52
	v_add_u32_e32 v48, 0x12000, v154
	v_and_b32_e32 v136, 0x1be00, v48
	v_ldexp_f32 v50, v50, v51
	v_mul_f32_e32 v50, 0x33800000, v50
	v_fmamk_f32 v50, v50, 0x39800000, v161
	v_cmp_gt_f32_e32 vcc, s64, v50
	v_mul_f32_e32 v51, 0x4b800000, v50
	v_lshl_add_u64 v[48:49], v[64:65], 0, v[136:137]
	v_cndmask_b32_e32 v50, v50, v51, vcc
	v_rsq_f32_e32 v50, v50
	v_lshl_add_u64 v[48:49], v[48:49], 0, s[26:27]
	v_lshl_add_u64 v[48:49], v[48:49], 0, v[148:149]
	v_mul_f32_e32 v51, 0x45800000, v50
	v_cndmask_b32_e32 v50, v50, v51, vcc
	v_pk_mul_f32 v[46:47], v[46:47], v[50:51] op_sel_hi:[1,0]
	v_pk_mul_f32 v[44:45], v[44:45], v[50:51] op_sel_hi:[1,0]
	v_pk_mul_f32 v[52:53], v[42:43], v[50:51] op_sel_hi:[1,0]
	v_pk_mul_f32 v[42:43], v[40:41], v[50:51] op_sel_hi:[1,0]
	v_cvt_pk_bf16_f32 v40, v44, v45
	v_cvt_pk_bf16_f32 v41, v46, v47
	v_pk_mul_f32 v[38:39], v[38:39], v[50:51] op_sel_hi:[1,0]
	v_cvt_pk_bf16_f32 v42, v42, v43
	v_cvt_pk_bf16_f32 v43, v52, v53
	global_store_dwordx4 v[48:49], v[40:43], off
	v_pk_mul_f32 v[36:37], v[36:37], v[50:51] op_sel_hi:[1,0]
	s_nop 0
	v_pk_mul_f32 v[40:41], v[34:35], v[50:51] op_sel_hi:[1,0]
	v_pk_mul_f32 v[34:35], v[32:33], v[50:51] op_sel_hi:[1,0]
	v_cvt_pk_bf16_f32 v32, v36, v37
	v_cvt_pk_bf16_f32 v33, v38, v39
	s_nop 0
	v_cvt_pk_bf16_f32 v34, v34, v35
	v_cvt_pk_bf16_f32 v35, v40, v41
	global_store_dwordx4 v[48:49], v[32:35], off offset:256
	s_waitcnt vmcnt(13)
	s_nop 1
	v_mov_b64_e32 v[34:35], v[182:183]
	v_ffbh_u32_e32 v36, v35
	v_min_u32_e32 v36, 32, v36
	v_lshlrev_b64 v[34:35], v36, v[34:35]
	v_min_u32_e32 v34, 1, v34
	v_or_b32_e32 v34, v35, v34
	v_cvt_f32_u32_e32 v34, v34
	v_sub_u32_e32 v35, 32, v36
	v_add_u32_e32 v32, 0x14000, v154
	v_and_b32_e32 v136, 0x1de00, v32
	v_ldexp_f32 v34, v34, v35
	v_mul_f32_e32 v34, 0x33800000, v34
	v_fmamk_f32 v34, v34, 0x39800000, v161
	v_cmp_gt_f32_e32 vcc, s64, v34
	v_mul_f32_e32 v35, 0x4b800000, v34
	v_lshl_add_u64 v[32:33], v[64:65], 0, v[136:137]
	v_cndmask_b32_e32 v34, v34, v35, vcc
	v_rsq_f32_e32 v34, v34
	v_lshl_add_u64 v[32:33], v[32:33], 0, s[26:27]
	v_lshl_add_u64 v[32:33], v[32:33], 0, v[148:149]
	v_mul_f32_e32 v35, 0x45800000, v34
	v_cndmask_b32_e32 v34, v34, v35, vcc
	v_pk_mul_f32 v[30:31], v[30:31], v[34:35] op_sel_hi:[1,0]
	v_pk_mul_f32 v[28:29], v[28:29], v[34:35] op_sel_hi:[1,0]
	v_pk_mul_f32 v[36:37], v[26:27], v[34:35] op_sel_hi:[1,0]
	v_pk_mul_f32 v[26:27], v[24:25], v[34:35] op_sel_hi:[1,0]
	v_cvt_pk_bf16_f32 v24, v28, v29
	v_cvt_pk_bf16_f32 v25, v30, v31
	v_pk_mul_f32 v[22:23], v[22:23], v[34:35] op_sel_hi:[1,0]
	v_cvt_pk_bf16_f32 v26, v26, v27
	v_cvt_pk_bf16_f32 v27, v36, v37
	global_store_dwordx4 v[32:33], v[24:27], off
	v_pk_mul_f32 v[20:21], v[20:21], v[34:35] op_sel_hi:[1,0]
	s_nop 0
	v_pk_mul_f32 v[24:25], v[18:19], v[34:35] op_sel_hi:[1,0]
	v_pk_mul_f32 v[18:19], v[16:17], v[34:35] op_sel_hi:[1,0]
	v_cvt_pk_bf16_f32 v16, v20, v21
	v_cvt_pk_bf16_f32 v17, v22, v23
	s_nop 0
	v_cvt_pk_bf16_f32 v18, v18, v19
	v_cvt_pk_bf16_f32 v19, v24, v25
	global_store_dwordx4 v[32:33], v[16:19], off offset:256
	s_waitcnt vmcnt(14)
	s_nop 1
	v_mov_b64_e32 v[18:19], v[184:185]
	v_ffbh_u32_e32 v20, v19
	v_min_u32_e32 v20, 32, v20
	v_lshlrev_b64 v[18:19], v20, v[18:19]
	v_min_u32_e32 v18, 1, v18
	v_or_b32_e32 v18, v19, v18
	v_cvt_f32_u32_e32 v18, v18
	v_sub_u32_e32 v19, 32, v20
	v_add_u32_e32 v16, 0x16000, v154
	v_and_b32_e32 v136, 0x1fe00, v16
	v_ldexp_f32 v18, v18, v19
	v_mul_f32_e32 v18, 0x33800000, v18
	v_fmamk_f32 v18, v18, 0x39800000, v161
	v_cmp_gt_f32_e32 vcc, s64, v18
	v_mul_f32_e32 v19, 0x4b800000, v18
	v_lshl_add_u64 v[16:17], v[64:65], 0, v[136:137]
	v_cndmask_b32_e32 v18, v18, v19, vcc
	v_rsq_f32_e32 v18, v18
	v_lshl_add_u64 v[16:17], v[16:17], 0, s[26:27]
	v_lshl_add_u64 v[16:17], v[16:17], 0, v[148:149]
	v_mul_f32_e32 v19, 0x45800000, v18
	v_cndmask_b32_e32 v18, v18, v19, vcc
	v_pk_mul_f32 v[14:15], v[14:15], v[18:19] op_sel_hi:[1,0]
	v_pk_mul_f32 v[12:13], v[12:13], v[18:19] op_sel_hi:[1,0]
	v_pk_mul_f32 v[20:21], v[10:11], v[18:19] op_sel_hi:[1,0]
	v_pk_mul_f32 v[10:11], v[8:9], v[18:19] op_sel_hi:[1,0]
	v_cvt_pk_bf16_f32 v8, v12, v13
	v_cvt_pk_bf16_f32 v9, v14, v15
	v_pk_mul_f32 v[6:7], v[6:7], v[18:19] op_sel_hi:[1,0]
	v_cvt_pk_bf16_f32 v10, v10, v11
	v_cvt_pk_bf16_f32 v11, v20, v21
	global_store_dwordx4 v[16:17], v[8:11], off
	v_pk_mul_f32 v[4:5], v[4:5], v[18:19] op_sel_hi:[1,0]
	s_nop 0
	v_pk_mul_f32 v[8:9], v[2:3], v[18:19] op_sel_hi:[1,0]
	v_pk_mul_f32 v[2:3], v[0:1], v[18:19] op_sel_hi:[1,0]
	v_cvt_pk_bf16_f32 v0, v4, v5
	v_cvt_pk_bf16_f32 v1, v6, v7
	s_nop 0
	v_cvt_pk_bf16_f32 v2, v2, v3
	v_cvt_pk_bf16_f32 v3, v8, v9
	global_store_dwordx4 v[16:17], v[0:3], off offset:256
	s_andn2_b64 vcc, exec, s[0:1]
	s_mov_b64 s[0:1], -1
	s_cbranch_vccnz .LBB0_1733
